# int8 SwiGLU epilogues: all 8 row-scale loads issued up front, per-group vmcnt(0) removed so stores stream (s_nop keeps store-data WAR distance)
# speedup vs baseline: 1.0059x; 1.0059x over previous
.LBB0_176:
	v_lshl_or_b32 v170, s54, 7, v154
	v_ashrrev_i32_e32 v171, 31, v170
	v_lshlrev_b64 v[144:145], 2, v[170:171]
	v_lshl_add_u64 v[146:147], s[40:41], 0, v[144:145]
	v_lshl_add_u64 v[144:145], s[6:7], 0, v[144:145]
	global_load_dwordx4 v[148:151], v[146:147], off
	global_load_dwordx4 v[158:161], v[144:145], off
	global_load_dwordx4 v[162:165], v[146:147], off offset:16
	global_load_dwordx4 v[166:169], v[144:145], off offset:16
	v_lshl_add_u32 v144, s64, 8, v152
	v_ashrrev_i32_e32 v145, 31, v144
	v_lshl_add_u64 v[146:147], v[144:145], 2, s[86:87]
	global_load_dword v172, v[146:147], off
	global_load_dword v224, v[146:147], off offset:64
	global_load_dword v226, v[146:147], off offset:128
	global_load_dword v228, v[146:147], off offset:192
	global_load_dword v230, v[146:147], off offset:512
	global_load_dword v232, v[146:147], off offset:576
	global_load_dword v234, v[146:147], off offset:640
	global_load_dword v236, v[146:147], off offset:704
	v_cvt_f32_i32_e32 v175, v120
	v_cvt_f32_i32_e32 v174, v124
	v_cvt_f32_i32_e32 v177, v121
	v_cvt_f32_i32_e32 v176, v125
	v_cvt_f32_i32_e32 v179, v122
	v_cvt_f32_i32_e32 v181, v123
	v_cvt_f32_i32_e32 v186, v118
	v_cvt_f32_i32_e32 v188, v119
	v_cvt_f32_i32_e32 v178, v126
	v_cvt_f32_i32_e32 v180, v127
	v_cvt_f32_i32_e32 v183, v112
	v_cvt_f32_i32_e32 v182, v116
	v_cvt_f32_i32_e32 v185, v113
	v_cvt_f32_i32_e32 v184, v117
	v_cvt_f32_i32_e32 v187, v114
	v_cvt_f32_i32_e32 v189, v115
	v_cvt_f32_i32_e32 v105, v105
	v_cvt_f32_i32_e32 v97, v97
	v_cvt_f32_i32_e32 v107, v107
	v_cvt_f32_i32_e32 v99, v99
	v_cvt_f32_i32_e32 v89, v89
	v_cvt_f32_i32_e32 v91, v91
	v_cvt_f32_i32_e32 v81, v81
	v_cvt_f32_i32_e32 v83, v83
	v_cvt_f32_i32_e32 v73, v73
	v_cvt_f32_i32_e32 v75, v75
	v_cvt_f32_i32_e32 v65, v65
	v_cvt_f32_i32_e32 v67, v67
	v_cvt_f32_i32_e32 v57, v57
	v_cvt_f32_i32_e32 v59, v59
	v_cvt_f32_i32_e32 v49, v49
	v_cvt_f32_i32_e32 v51, v51
	v_cvt_f32_i32_e32 v41, v41
	v_cvt_f32_i32_e32 v43, v43
	v_cvt_f32_i32_e32 v33, v33
	v_cvt_f32_i32_e32 v35, v35
	v_cvt_f32_i32_e32 v25, v25
	v_cvt_f32_i32_e32 v27, v27
	v_cvt_f32_i32_e32 v17, v17
	v_cvt_f32_i32_e32 v19, v19
	v_cvt_f32_i32_e32 v9, v9
	v_cvt_f32_i32_e32 v11, v11
	v_cvt_f32_i32_e32 v1, v1
	v_cvt_f32_i32_e32 v3, v3
	s_andn2_b64 vcc, exec, s[0:1]
	s_mov_b64 s[0:1], -1
	s_waitcnt vmcnt(0)
	v_pk_mul_f32 v[118:119], v[158:159], s[22:23] op_sel_hi:[1,0]
	v_pk_mul_f32 v[122:123], v[148:149], s[22:23] op_sel_hi:[1,0]
	v_mov_b32_e32 v121, v118
	v_mov_b32_e32 v120, v122
	v_pk_mul_f32 v[124:125], v[150:151], s[22:23] op_sel_hi:[1,0]
	v_mov_b32_e32 v118, v123
	v_pk_mul_f32 v[150:151], v[120:121], v[172:173] op_sel_hi:[1,0]
	v_pk_mul_f32 v[114:115], v[160:161], s[22:23] op_sel_hi:[1,0]
	v_pk_mul_f32 v[126:127], v[162:163], s[22:23] op_sel_hi:[1,0]
	v_pk_mul_f32 v[112:113], v[168:169], s[22:23] op_sel_hi:[1,0]
	v_pk_mul_f32 v[116:117], v[166:167], s[22:23] op_sel_hi:[1,0]
	v_pk_mul_f32 v[158:159], v[118:119], v[172:173] op_sel_hi:[1,0]
	v_pk_mul_f32 v[150:151], v[150:151], v[174:175]
	v_pk_mul_f32 v[148:149], v[164:165], s[22:23] op_sel_hi:[1,0]
	v_mov_b32_e32 v122, v124
	v_mov_b32_e32 v123, v114
	v_mov_b32_e32 v114, v125
	v_mov_b32_e32 v125, v116
	v_mov_b32_e32 v116, v127
	v_mov_b32_e32 v127, v112
	v_pk_mul_f32 v[158:159], v[158:159], v[176:177]
	v_mul_f32_e32 v112, 0xbfb8aa3b, v150
	v_mov_b32_e32 v124, v126
	v_mov_b32_e32 v126, v148
	v_pk_mul_f32 v[160:161], v[122:123], v[172:173] op_sel_hi:[1,0]
	v_mul_f32_e32 v148, 0xbfb8aa3b, v158
	v_exp_f32_e32 v112, v112
	v_pk_mul_f32 v[160:161], v[160:161], v[178:179]
	v_exp_f32_e32 v148, v148
	v_mul_f32_e32 v145, v150, v151
	v_mul_f32_e32 v151, 0xbfb8aa3b, v160
	v_exp_f32_e32 v151, v151
	v_add_f32_e32 v112, 1.0, v112
	v_add_f32_e32 v148, 1.0, v148
	v_rcp_f32_e32 v112, v112
	v_pk_mul_f32 v[162:163], v[114:115], v[172:173] op_sel_hi:[1,0]
	v_pk_mul_f32 v[164:165], v[124:125], v[172:173] op_sel_hi:[1,0]
	v_rcp_f32_e32 v148, v148
	v_pk_mul_f32 v[162:163], v[162:163], v[180:181]
	v_pk_mul_f32 v[164:165], v[164:165], v[182:183]
	v_add_f32_e32 v151, 1.0, v151
	v_mul_f32_e32 v150, v158, v159
	v_mul_f32_e32 v158, v160, v161
	v_mul_f32_e32 v159, 0xbfb8aa3b, v162
	v_mul_f32_e32 v161, 0xbfb8aa3b, v164
	v_rcp_f32_e32 v151, v151
	v_exp_f32_e32 v159, v159
	v_exp_f32_e32 v161, v161
	v_mul_f32_e32 v145, v145, v112
	v_mov_b32_e32 v112, v149
	v_pk_mul_f32 v[166:167], v[116:117], v[172:173] op_sel_hi:[1,0]
	v_mul_f32_e32 v150, v150, v148
	v_pk_mul_f32 v[148:149], v[112:113], v[172:173] op_sel_hi:[1,0]
	v_pk_mul_f32 v[168:169], v[126:127], v[172:173] op_sel_hi:[1,0]
	v_pk_mul_f32 v[166:167], v[166:167], v[184:185]
	v_pk_mul_f32 v[148:149], v[148:149], v[188:189]
	v_pk_mul_f32 v[168:169], v[168:169], v[186:187]
	v_mul_f32_e32 v160, v162, v163
	v_mul_f32_e32 v163, 0xbfb8aa3b, v166
	v_mul_f32_e32 v151, v158, v151
	v_mul_f32_e32 v158, 0xbfb8aa3b, v148
	v_mul_f32_e32 v162, v164, v165
	v_mul_f32_e32 v165, 0xbfb8aa3b, v168
	v_exp_f32_e32 v163, v163
	v_add_f32_e32 v159, 1.0, v159
	v_add_f32_e32 v161, 1.0, v161
	v_exp_f32_e32 v158, v158
	v_exp_f32_e32 v165, v165
	v_rcp_f32_e32 v159, v159
	v_rcp_f32_e32 v161, v161
	v_add_f32_e32 v163, 1.0, v163
	v_add_f32_e32 v158, 1.0, v158
	v_rcp_f32_e32 v163, v163
	v_mul_f32_e32 v159, v160, v159
	v_mul_f32_e32 v160, v162, v161
	v_add_f32_e32 v162, 1.0, v165
	v_rcp_f32_e32 v158, v158
	v_rcp_f32_e32 v162, v162
	v_mul_f32_e32 v164, v166, v167
	v_mul_f32_e32 v148, v148, v149
	v_mul_f32_e32 v161, v164, v163
	v_mul_f32_e32 v163, v168, v169
	v_mul_f32_e32 v148, v148, v158
	v_mul_f32_e32 v162, v163, v162
	v_cvt_pk_bf16_f32 v158, v145, v150
	v_cvt_pk_bf16_f32 v159, v151, v159
	v_cvt_pk_bf16_f32 v160, v160, v161
	v_cvt_pk_bf16_f32 v161, v162, v148
	v_mov_b64_e32 v[148:149], s[82:83]
	v_mad_i64_i32 v[162:163], s[54:55], v144, s53, v[148:149]
	v_lshlrev_b64 v[150:151], 1, v[170:171]
	v_lshl_add_u64 v[162:163], v[162:163], 0, v[150:151]
	global_store_dwordx4 v[162:163], v[158:161], off
	v_cvt_f32_i32_e32 v163, v104
	v_cvt_f32_i32_e32 v162, v108
	v_or_b32_e32 v158, 16, v144
	v_ashrrev_i32_e32 v159, 31, v158
	v_lshl_add_u64 v[160:161], v[158:159], 2, s[86:87]
	s_nop 1
	v_cvt_f32_i32_e32 v104, v109
	v_cvt_f32_i32_e32 v109, v106
	v_cvt_f32_i32_e32 v106, v111
	v_cvt_f32_i32_e32 v111, v96
	v_cvt_f32_i32_e32 v96, v101
	v_cvt_f32_i32_e32 v108, v110
	v_cvt_f32_i32_e32 v110, v100
	v_cvt_f32_i32_e32 v101, v98
	v_cvt_f32_i32_e32 v100, v102
	v_cvt_f32_i32_e32 v98, v103
	v_pk_mul_f32 v[102:103], v[120:121], v[224:225] op_sel_hi:[1,0]
	v_pk_mul_f32 v[164:165], v[118:119], v[224:225] op_sel_hi:[1,0]
	v_pk_mul_f32 v[172:173], v[116:117], v[224:225] op_sel_hi:[1,0]
	v_pk_mul_f32 v[102:103], v[102:103], v[162:163]
	v_pk_mul_f32 v[104:105], v[164:165], v[104:105]
	v_pk_mul_f32 v[96:97], v[172:173], v[96:97]
	v_mul_f32_e32 v145, 0xbfb8aa3b, v102
	v_mul_f32_e32 v102, v102, v103
	v_mul_f32_e32 v103, 0xbfb8aa3b, v104
	v_mul_f32_e32 v159, v96, v97
	v_exp_f32_e32 v97, v145
	v_exp_f32_e32 v103, v103
	v_pk_mul_f32 v[166:167], v[122:123], v[224:225] op_sel_hi:[1,0]
	v_pk_mul_f32 v[168:169], v[114:115], v[224:225] op_sel_hi:[1,0]
	v_pk_mul_f32 v[170:171], v[124:125], v[224:225] op_sel_hi:[1,0]
	v_pk_mul_f32 v[174:175], v[126:127], v[224:225] op_sel_hi:[1,0]
	v_pk_mul_f32 v[108:109], v[166:167], v[108:109]
	v_pk_mul_f32 v[106:107], v[168:169], v[106:107]
	v_pk_mul_f32 v[110:111], v[170:171], v[110:111]
	v_pk_mul_f32 v[100:101], v[174:175], v[100:101]
	v_mul_f32_e32 v104, v104, v105
	v_mul_f32_e32 v105, 0xbfb8aa3b, v108
	v_mul_f32_e32 v108, v108, v109
	v_mul_f32_e32 v109, 0xbfb8aa3b, v106
	v_mul_f32_e32 v106, v106, v107
	v_mul_f32_e32 v107, 0xbfb8aa3b, v110
	v_mul_f32_e32 v110, v110, v111
	v_mul_f32_e32 v111, 0xbfb8aa3b, v96
	v_mul_f32_e32 v96, 0xbfb8aa3b, v100
	v_exp_f32_e32 v145, v96
	v_add_f32_e32 v96, 1.0, v97
	v_add_f32_e32 v97, 1.0, v103
	v_rcp_f32_e32 v96, v96
	v_rcp_f32_e32 v97, v97
	v_exp_f32_e32 v105, v105
	v_exp_f32_e32 v109, v109
	v_exp_f32_e32 v107, v107
	v_mul_f32_e32 v102, v102, v96
	v_mul_f32_e32 v104, v104, v97
	v_pk_mul_f32 v[96:97], v[112:113], v[224:225] op_sel_hi:[1,0]
	v_add_f32_e32 v103, 1.0, v105
	v_pk_mul_f32 v[96:97], v[96:97], v[98:99]
	v_add_f32_e32 v105, 1.0, v109
	v_add_f32_e32 v107, 1.0, v107
	v_mul_f32_e32 v98, 0xbfb8aa3b, v96
	v_exp_f32_e32 v111, v111
	v_rcp_f32_e32 v105, v105
	v_rcp_f32_e32 v107, v107
	v_exp_f32_e32 v98, v98
	v_add_f32_e32 v109, 1.0, v111
	v_mul_f32_e32 v105, v106, v105
	v_mul_f32_e32 v106, v110, v107
	v_add_f32_e32 v107, 1.0, v145
	v_add_f32_e32 v98, 1.0, v98
	v_rcp_f32_e32 v109, v109
	v_rcp_f32_e32 v107, v107
	v_rcp_f32_e32 v98, v98
	v_rcp_f32_e32 v103, v103
	v_mul_f32_e32 v100, v100, v101
	v_mul_f32_e32 v96, v96, v97
	v_mul_f32_e32 v99, v159, v109
	v_mul_f32_e32 v100, v100, v107
	v_mul_f32_e32 v101, v96, v98
	v_mul_f32_e32 v103, v108, v103
	v_cvt_pk_bf16_f32 v96, v102, v104
	v_cvt_pk_bf16_f32 v97, v103, v105
	v_cvt_pk_bf16_f32 v98, v106, v99
	v_cvt_pk_bf16_f32 v99, v100, v101
	v_mad_i64_i32 v[100:101], s[54:55], v158, s53, v[148:149]
	v_lshl_add_u64 v[100:101], v[100:101], 0, v[150:151]
	global_store_dwordx4 v[100:101], v[96:99], off
	v_cvt_f32_i32_e32 v101, v88
	v_cvt_f32_i32_e32 v100, v92
	v_or_b32_e32 v96, 32, v144
	v_ashrrev_i32_e32 v97, 31, v96
	v_lshl_add_u64 v[98:99], v[96:97], 2, s[86:87]
	s_nop 1
	v_cvt_f32_i32_e32 v88, v93
	v_cvt_f32_i32_e32 v93, v90
	v_cvt_f32_i32_e32 v92, v94
	v_cvt_f32_i32_e32 v90, v95
	v_cvt_f32_i32_e32 v95, v80
	v_cvt_f32_i32_e32 v94, v84
	v_cvt_f32_i32_e32 v80, v85
	v_cvt_f32_i32_e32 v85, v82
	v_cvt_f32_i32_e32 v84, v86
	v_cvt_f32_i32_e32 v82, v87
	v_pk_mul_f32 v[86:87], v[120:121], v[226:227] op_sel_hi:[1,0]
	v_pk_mul_f32 v[102:103], v[118:119], v[226:227] op_sel_hi:[1,0]
	v_pk_mul_f32 v[104:105], v[122:123], v[226:227] op_sel_hi:[1,0]
	v_pk_mul_f32 v[106:107], v[114:115], v[226:227] op_sel_hi:[1,0]
	v_pk_mul_f32 v[108:109], v[124:125], v[226:227] op_sel_hi:[1,0]
	v_pk_mul_f32 v[86:87], v[86:87], v[100:101]
	v_pk_mul_f32 v[88:89], v[102:103], v[88:89]
	v_pk_mul_f32 v[92:93], v[104:105], v[92:93]
	v_pk_mul_f32 v[90:91], v[106:107], v[90:91]
	v_pk_mul_f32 v[94:95], v[108:109], v[94:95]
	v_mul_f32_e32 v97, 0xbfb8aa3b, v86
	v_mul_f32_e32 v86, v86, v87
	v_mul_f32_e32 v87, 0xbfb8aa3b, v88
	v_mul_f32_e32 v88, v88, v89
	v_mul_f32_e32 v89, 0xbfb8aa3b, v92
	v_mul_f32_e32 v92, v92, v93
	v_mul_f32_e32 v93, 0xbfb8aa3b, v90
	v_mul_f32_e32 v90, v90, v91
	v_mul_f32_e32 v91, 0xbfb8aa3b, v94
	v_pk_mul_f32 v[110:111], v[116:117], v[226:227] op_sel_hi:[1,0]
	v_exp_f32_e32 v87, v87
	v_exp_f32_e32 v89, v89
	v_exp_f32_e32 v93, v93
	v_exp_f32_e32 v91, v91
	v_pk_mul_f32 v[80:81], v[110:111], v[80:81]
	v_mul_f32_e32 v94, v94, v95
	v_mul_f32_e32 v95, 0xbfb8aa3b, v80
	v_exp_f32_e32 v95, v95
	v_add_f32_e32 v87, 1.0, v87
	v_add_f32_e32 v89, 1.0, v89
	v_add_f32_e32 v93, 1.0, v93
	v_add_f32_e32 v91, 1.0, v91
	v_pk_mul_f32 v[158:159], v[126:127], v[226:227] op_sel_hi:[1,0]
	v_rcp_f32_e32 v87, v87
	v_rcp_f32_e32 v89, v89
	v_rcp_f32_e32 v93, v93
	v_rcp_f32_e32 v91, v91
	v_pk_mul_f32 v[98:99], v[112:113], v[226:227] op_sel_hi:[1,0]
	v_pk_mul_f32 v[84:85], v[158:159], v[84:85]
	v_pk_mul_f32 v[82:83], v[98:99], v[82:83]
	v_mul_f32_e32 v80, v80, v81
	v_mul_f32_e32 v81, 0xbfb8aa3b, v84
	v_add_f32_e32 v95, 1.0, v95
	v_mul_f32_e32 v98, 0xbfb8aa3b, v82
	v_exp_f32_e32 v81, v81
	v_rcp_f32_e32 v95, v95
	v_mul_f32_e32 v87, v88, v87
	v_mul_f32_e32 v88, v92, v89
	v_mul_f32_e32 v89, v90, v93
	v_mul_f32_e32 v90, v94, v91
	v_exp_f32_e32 v91, v98
	v_exp_f32_e32 v97, v97
	v_mul_f32_e32 v92, v80, v95
	v_add_f32_e32 v80, 1.0, v81
	v_rcp_f32_e32 v80, v80
	v_add_f32_e32 v81, 1.0, v91
	v_add_f32_e32 v97, 1.0, v97
	v_rcp_f32_e32 v81, v81
	v_rcp_f32_e32 v97, v97
	v_mul_f32_e32 v84, v84, v85
	v_mul_f32_e32 v84, v84, v80
	v_mul_f32_e32 v80, v82, v83
	v_mul_f32_e32 v83, v80, v81
	v_mul_f32_e32 v86, v86, v97
	v_cvt_pk_bf16_f32 v80, v86, v87
	v_cvt_pk_bf16_f32 v81, v88, v89
	v_cvt_pk_bf16_f32 v82, v90, v92
	v_cvt_pk_bf16_f32 v83, v84, v83
	v_mad_i64_i32 v[84:85], s[54:55], v96, s53, v[148:149]
	v_lshl_add_u64 v[84:85], v[84:85], 0, v[150:151]
	global_store_dwordx4 v[84:85], v[80:83], off
	v_cvt_f32_i32_e32 v85, v72
	v_cvt_f32_i32_e32 v84, v76
	v_or_b32_e32 v80, 48, v144
	v_ashrrev_i32_e32 v81, 31, v80
	v_lshl_add_u64 v[82:83], v[80:81], 2, s[86:87]
	s_nop 1
	v_cvt_f32_i32_e32 v72, v77
	v_cvt_f32_i32_e32 v77, v74
	v_cvt_f32_i32_e32 v76, v78
	v_cvt_f32_i32_e32 v74, v79
	v_cvt_f32_i32_e32 v79, v64
	v_cvt_f32_i32_e32 v78, v68
	v_cvt_f32_i32_e32 v64, v69
	v_cvt_f32_i32_e32 v69, v66
	v_cvt_f32_i32_e32 v68, v70
	v_cvt_f32_i32_e32 v66, v71
	v_pk_mul_f32 v[70:71], v[120:121], v[228:229] op_sel_hi:[1,0]
	v_pk_mul_f32 v[86:87], v[118:119], v[228:229] op_sel_hi:[1,0]
	v_pk_mul_f32 v[88:89], v[122:123], v[228:229] op_sel_hi:[1,0]
	v_pk_mul_f32 v[90:91], v[114:115], v[228:229] op_sel_hi:[1,0]
	v_pk_mul_f32 v[92:93], v[124:125], v[228:229] op_sel_hi:[1,0]
	v_pk_mul_f32 v[94:95], v[116:117], v[228:229] op_sel_hi:[1,0]
	v_pk_mul_f32 v[70:71], v[70:71], v[84:85]
	v_pk_mul_f32 v[72:73], v[86:87], v[72:73]
	v_pk_mul_f32 v[76:77], v[88:89], v[76:77]
	v_pk_mul_f32 v[74:75], v[90:91], v[74:75]
	v_pk_mul_f32 v[78:79], v[92:93], v[78:79]
	v_pk_mul_f32 v[64:65], v[94:95], v[64:65]
	v_mul_f32_e32 v81, 0xbfb8aa3b, v70
	v_mul_f32_e32 v70, v70, v71
	v_mul_f32_e32 v71, 0xbfb8aa3b, v72
	v_mul_f32_e32 v72, v72, v73
	v_mul_f32_e32 v73, 0xbfb8aa3b, v76
	v_mul_f32_e32 v76, v76, v77
	v_mul_f32_e32 v77, 0xbfb8aa3b, v74
	v_mul_f32_e32 v74, v74, v75
	v_mul_f32_e32 v75, 0xbfb8aa3b, v78
	v_mul_f32_e32 v78, v78, v79
	v_mul_f32_e32 v79, 0xbfb8aa3b, v64
	v_exp_f32_e32 v71, v71
	v_exp_f32_e32 v73, v73
	v_exp_f32_e32 v77, v77
	v_exp_f32_e32 v75, v75
	v_exp_f32_e32 v79, v79
	v_pk_mul_f32 v[96:97], v[126:127], v[228:229] op_sel_hi:[1,0]
	v_pk_mul_f32 v[82:83], v[112:113], v[228:229] op_sel_hi:[1,0]
	v_pk_mul_f32 v[68:69], v[96:97], v[68:69]
	v_pk_mul_f32 v[66:67], v[82:83], v[66:67]
	v_mul_f32_e32 v64, v64, v65
	v_mul_f32_e32 v65, 0xbfb8aa3b, v68
	v_mul_f32_e32 v82, 0xbfb8aa3b, v66
	v_exp_f32_e32 v65, v65
	v_add_f32_e32 v71, 1.0, v71
	v_add_f32_e32 v73, 1.0, v73
	v_add_f32_e32 v77, 1.0, v77
	v_add_f32_e32 v75, 1.0, v75
	v_add_f32_e32 v79, 1.0, v79
	v_exp_f32_e32 v82, v82
	v_rcp_f32_e32 v71, v71
	v_rcp_f32_e32 v73, v73
	v_rcp_f32_e32 v77, v77
	v_rcp_f32_e32 v75, v75
	v_rcp_f32_e32 v79, v79
	v_exp_f32_e32 v81, v81
	v_add_f32_e32 v65, 1.0, v65
	v_mul_f32_e32 v71, v72, v71
	v_mul_f32_e32 v72, v76, v73
	v_mul_f32_e32 v73, v74, v77
	v_mul_f32_e32 v74, v78, v75
	v_mul_f32_e32 v75, v64, v79
	v_rcp_f32_e32 v64, v65
	v_add_f32_e32 v65, 1.0, v82
	v_add_f32_e32 v81, 1.0, v81
	v_rcp_f32_e32 v65, v65
	v_rcp_f32_e32 v81, v81
	v_mul_f32_e32 v68, v68, v69
	v_mul_f32_e32 v68, v68, v64
	v_mul_f32_e32 v64, v66, v67
	v_mul_f32_e32 v67, v64, v65
	v_mul_f32_e32 v70, v70, v81
	v_cvt_pk_bf16_f32 v64, v70, v71
	v_cvt_pk_bf16_f32 v65, v72, v73
	v_cvt_pk_bf16_f32 v66, v74, v75
	v_cvt_pk_bf16_f32 v67, v68, v67
	v_mad_i64_i32 v[68:69], s[54:55], v80, s53, v[148:149]
	v_lshl_add_u64 v[68:69], v[68:69], 0, v[150:151]
	global_store_dwordx4 v[68:69], v[64:67], off
	s_nop 1
	v_add_u32_e32 v80, 0x80, v144
	v_cvt_f32_i32_e32 v67, v56
	v_cvt_f32_i32_e32 v66, v60
	v_cvt_f32_i32_e32 v56, v61
	v_cvt_f32_i32_e32 v61, v58
	v_cvt_f32_i32_e32 v60, v62
	v_cvt_f32_i32_e32 v58, v63
	v_cvt_f32_i32_e32 v63, v48
	v_cvt_f32_i32_e32 v62, v52
	v_cvt_f32_i32_e32 v48, v53
	v_cvt_f32_i32_e32 v53, v50
	v_cvt_f32_i32_e32 v52, v54
	v_cvt_f32_i32_e32 v50, v55
	v_pk_mul_f32 v[54:55], v[120:121], v[230:231] op_sel_hi:[1,0]
	v_pk_mul_f32 v[68:69], v[118:119], v[230:231] op_sel_hi:[1,0]
	v_pk_mul_f32 v[70:71], v[122:123], v[230:231] op_sel_hi:[1,0]
	v_pk_mul_f32 v[72:73], v[114:115], v[230:231] op_sel_hi:[1,0]
	v_pk_mul_f32 v[74:75], v[124:125], v[230:231] op_sel_hi:[1,0]
	v_pk_mul_f32 v[76:77], v[116:117], v[230:231] op_sel_hi:[1,0]
	v_pk_mul_f32 v[78:79], v[126:127], v[230:231] op_sel_hi:[1,0]
	v_pk_mul_f32 v[64:65], v[112:113], v[230:231] op_sel_hi:[1,0]
	v_pk_mul_f32 v[54:55], v[54:55], v[66:67]
	v_pk_mul_f32 v[56:57], v[68:69], v[56:57]
	v_pk_mul_f32 v[60:61], v[70:71], v[60:61]
	v_pk_mul_f32 v[58:59], v[72:73], v[58:59]
	v_pk_mul_f32 v[62:63], v[74:75], v[62:63]
	v_pk_mul_f32 v[48:49], v[76:77], v[48:49]
	v_pk_mul_f32 v[52:53], v[78:79], v[52:53]
	v_pk_mul_f32 v[50:51], v[64:65], v[50:51]
	v_mul_f32_e32 v64, 0xbfb8aa3b, v54
	v_mul_f32_e32 v54, v54, v55
	v_mul_f32_e32 v55, 0xbfb8aa3b, v56
	v_mul_f32_e32 v56, v56, v57
	v_mul_f32_e32 v57, 0xbfb8aa3b, v60
	v_mul_f32_e32 v60, v60, v61
	v_mul_f32_e32 v61, 0xbfb8aa3b, v58
	v_mul_f32_e32 v58, v58, v59
	v_mul_f32_e32 v59, 0xbfb8aa3b, v62
	v_mul_f32_e32 v62, v62, v63
	v_mul_f32_e32 v63, 0xbfb8aa3b, v48
	v_mul_f32_e32 v48, v48, v49
	v_mul_f32_e32 v49, 0xbfb8aa3b, v52
	v_mul_f32_e32 v52, v52, v53
	v_mul_f32_e32 v53, 0xbfb8aa3b, v50
	v_exp_f32_e32 v55, v55
	v_exp_f32_e32 v57, v57
	v_exp_f32_e32 v61, v61
	v_exp_f32_e32 v59, v59
	v_exp_f32_e32 v63, v63
	v_exp_f32_e32 v49, v49
	v_exp_f32_e32 v53, v53
	v_exp_f32_e32 v64, v64
	v_add_f32_e32 v55, 1.0, v55
	v_add_f32_e32 v57, 1.0, v57
	v_add_f32_e32 v61, 1.0, v61
	v_add_f32_e32 v59, 1.0, v59
	v_add_f32_e32 v63, 1.0, v63
	v_add_f32_e32 v49, 1.0, v49
	v_add_f32_e32 v53, 1.0, v53
	v_rcp_f32_e32 v55, v55
	v_rcp_f32_e32 v57, v57
	v_rcp_f32_e32 v61, v61
	v_rcp_f32_e32 v59, v59
	v_rcp_f32_e32 v63, v63
	v_add_f32_e32 v64, 1.0, v64
	v_rcp_f32_e32 v49, v49
	v_rcp_f32_e32 v53, v53
	v_rcp_f32_e32 v64, v64
	v_mul_f32_e32 v55, v56, v55
	v_mul_f32_e32 v56, v60, v57
	v_mul_f32_e32 v57, v58, v61
	v_mul_f32_e32 v58, v62, v59
	v_mul_f32_e32 v59, v48, v63
	v_mul_f32_e32 v48, v50, v51
	v_mul_f32_e32 v52, v52, v49
	v_mul_f32_e32 v51, v48, v53
	v_mul_f32_e32 v54, v54, v64
	v_cvt_pk_bf16_f32 v48, v54, v55
	v_cvt_pk_bf16_f32 v49, v56, v57
	v_cvt_pk_bf16_f32 v50, v58, v59
	v_cvt_pk_bf16_f32 v51, v52, v51
	v_mad_i64_i32 v[52:53], s[54:55], v80, s53, v[148:149]
	v_lshl_add_u64 v[52:53], v[52:53], 0, v[150:151]
	global_store_dwordx4 v[52:53], v[48:51], off
	s_nop 1
	v_add_u32_e32 v64, 0x90, v144
	v_cvt_f32_i32_e32 v51, v40
	v_cvt_f32_i32_e32 v50, v44
	v_cvt_f32_i32_e32 v40, v45
	v_cvt_f32_i32_e32 v45, v42
	v_cvt_f32_i32_e32 v44, v46
	v_cvt_f32_i32_e32 v42, v47
	v_cvt_f32_i32_e32 v47, v32
	v_cvt_f32_i32_e32 v46, v36
	v_cvt_f32_i32_e32 v32, v37
	v_cvt_f32_i32_e32 v37, v34
	v_cvt_f32_i32_e32 v36, v38
	v_cvt_f32_i32_e32 v34, v39
	v_pk_mul_f32 v[38:39], v[120:121], v[232:233] op_sel_hi:[1,0]
	v_pk_mul_f32 v[52:53], v[118:119], v[232:233] op_sel_hi:[1,0]
	v_pk_mul_f32 v[54:55], v[122:123], v[232:233] op_sel_hi:[1,0]
	v_pk_mul_f32 v[56:57], v[114:115], v[232:233] op_sel_hi:[1,0]
	v_pk_mul_f32 v[58:59], v[124:125], v[232:233] op_sel_hi:[1,0]
	v_pk_mul_f32 v[60:61], v[116:117], v[232:233] op_sel_hi:[1,0]
	v_pk_mul_f32 v[62:63], v[126:127], v[232:233] op_sel_hi:[1,0]
	v_pk_mul_f32 v[48:49], v[112:113], v[232:233] op_sel_hi:[1,0]
	v_pk_mul_f32 v[38:39], v[38:39], v[50:51]
	v_pk_mul_f32 v[40:41], v[52:53], v[40:41]
	v_pk_mul_f32 v[44:45], v[54:55], v[44:45]
	v_pk_mul_f32 v[42:43], v[56:57], v[42:43]
	v_pk_mul_f32 v[46:47], v[58:59], v[46:47]
	v_pk_mul_f32 v[32:33], v[60:61], v[32:33]
	v_pk_mul_f32 v[36:37], v[62:63], v[36:37]
	v_pk_mul_f32 v[34:35], v[48:49], v[34:35]
	v_mul_f32_e32 v48, 0xbfb8aa3b, v38
	v_mul_f32_e32 v38, v38, v39
	v_mul_f32_e32 v39, 0xbfb8aa3b, v40
	v_mul_f32_e32 v40, v40, v41
	v_mul_f32_e32 v41, 0xbfb8aa3b, v44
	v_mul_f32_e32 v44, v44, v45
	v_mul_f32_e32 v45, 0xbfb8aa3b, v42
	v_mul_f32_e32 v42, v42, v43
	v_mul_f32_e32 v43, 0xbfb8aa3b, v46
	v_mul_f32_e32 v46, v46, v47
	v_mul_f32_e32 v47, 0xbfb8aa3b, v32
	v_mul_f32_e32 v32, v32, v33
	v_mul_f32_e32 v33, 0xbfb8aa3b, v36
	v_mul_f32_e32 v36, v36, v37
	v_mul_f32_e32 v37, 0xbfb8aa3b, v34
	v_mul_f32_e32 v34, v34, v35
	v_exp_f32_e32 v35, v48
	v_exp_f32_e32 v33, v33
	v_exp_f32_e32 v37, v37
	v_exp_f32_e32 v39, v39
	v_exp_f32_e32 v41, v41
	v_exp_f32_e32 v45, v45
	v_exp_f32_e32 v43, v43
	v_exp_f32_e32 v47, v47
	v_add_f32_e32 v35, 1.0, v35
	v_add_f32_e32 v33, 1.0, v33
	v_add_f32_e32 v37, 1.0, v37
	v_add_f32_e32 v39, 1.0, v39
	v_add_f32_e32 v41, 1.0, v41
	v_add_f32_e32 v45, 1.0, v45
	v_add_f32_e32 v43, 1.0, v43
	v_add_f32_e32 v47, 1.0, v47
	v_rcp_f32_e32 v35, v35
	v_rcp_f32_e32 v33, v33
	v_rcp_f32_e32 v37, v37
	v_rcp_f32_e32 v39, v39
	v_rcp_f32_e32 v41, v41
	v_rcp_f32_e32 v45, v45
	v_rcp_f32_e32 v43, v43
	v_rcp_f32_e32 v47, v47
	v_mul_f32_e32 v35, v38, v35
	v_mul_f32_e32 v36, v36, v33
	v_mul_f32_e32 v37, v34, v37
	v_mul_f32_e32 v38, v40, v39
	v_mul_f32_e32 v39, v44, v41
	v_mul_f32_e32 v40, v42, v45
	v_mul_f32_e32 v41, v46, v43
	v_mul_f32_e32 v42, v32, v47
	v_cvt_pk_bf16_f32 v32, v35, v38
	v_cvt_pk_bf16_f32 v33, v39, v40
	v_cvt_pk_bf16_f32 v34, v41, v42
	v_cvt_pk_bf16_f32 v35, v36, v37
	v_mad_i64_i32 v[36:37], s[54:55], v64, s53, v[148:149]
	v_lshl_add_u64 v[36:37], v[36:37], 0, v[150:151]
	global_store_dwordx4 v[36:37], v[32:35], off
	s_nop 1
	v_pk_mul_f32 v[36:37], v[120:121], v[234:235] op_sel_hi:[1,0]
	v_cvt_f32_i32_e32 v35, v24
	v_cvt_f32_i32_e32 v34, v28
	v_cvt_f32_i32_e32 v24, v29
	v_cvt_f32_i32_e32 v29, v26
	v_cvt_f32_i32_e32 v28, v30
	v_cvt_f32_i32_e32 v26, v31
	v_cvt_f32_i32_e32 v31, v16
	v_cvt_f32_i32_e32 v30, v20
	v_cvt_f32_i32_e32 v16, v21
	v_cvt_f32_i32_e32 v21, v18
	v_cvt_f32_i32_e32 v20, v22
	v_cvt_f32_i32_e32 v18, v23
	v_pk_mul_f32 v[38:39], v[118:119], v[234:235] op_sel_hi:[1,0]
	v_pk_mul_f32 v[40:41], v[122:123], v[234:235] op_sel_hi:[1,0]
	v_pk_mul_f32 v[42:43], v[114:115], v[234:235] op_sel_hi:[1,0]
	v_pk_mul_f32 v[44:45], v[124:125], v[234:235] op_sel_hi:[1,0]
	v_pk_mul_f32 v[46:47], v[116:117], v[234:235] op_sel_hi:[1,0]
	v_pk_mul_f32 v[48:49], v[126:127], v[234:235] op_sel_hi:[1,0]
	v_pk_mul_f32 v[32:33], v[112:113], v[234:235] op_sel_hi:[1,0]
	v_pk_mul_f32 v[34:35], v[36:37], v[34:35]
	v_pk_mul_f32 v[24:25], v[38:39], v[24:25]
	v_pk_mul_f32 v[28:29], v[40:41], v[28:29]
	v_pk_mul_f32 v[26:27], v[42:43], v[26:27]
	v_pk_mul_f32 v[30:31], v[44:45], v[30:31]
	v_pk_mul_f32 v[16:17], v[46:47], v[16:17]
	v_pk_mul_f32 v[20:21], v[48:49], v[20:21]
	v_pk_mul_f32 v[18:19], v[32:33], v[18:19]
	v_mul_f32_e32 v32, 0xbfb8aa3b, v34
	v_mul_f32_e32 v33, v34, v35
	v_mul_f32_e32 v34, 0xbfb8aa3b, v24
	v_mul_f32_e32 v24, v24, v25
	v_mul_f32_e32 v25, 0xbfb8aa3b, v28
	v_mul_f32_e32 v28, v28, v29
	v_mul_f32_e32 v29, 0xbfb8aa3b, v26
	v_mul_f32_e32 v26, v26, v27
	v_mul_f32_e32 v27, 0xbfb8aa3b, v30
	v_mul_f32_e32 v30, v30, v31
	v_mul_f32_e32 v31, 0xbfb8aa3b, v16
	v_mul_f32_e32 v16, v16, v17
	v_mul_f32_e32 v17, 0xbfb8aa3b, v20
	v_mul_f32_e32 v20, v20, v21
	v_mul_f32_e32 v21, 0xbfb8aa3b, v18
	v_mul_f32_e32 v18, v18, v19
	v_exp_f32_e32 v19, v32
	v_exp_f32_e32 v32, v34
	v_exp_f32_e32 v25, v25
	v_exp_f32_e32 v29, v29
	v_exp_f32_e32 v27, v27
	v_exp_f32_e32 v31, v31
	v_exp_f32_e32 v17, v17
	v_exp_f32_e32 v21, v21
	v_add_f32_e32 v19, 1.0, v19
	v_add_f32_e32 v32, 1.0, v32
	v_add_f32_e32 v25, 1.0, v25
	v_add_f32_e32 v29, 1.0, v29
	v_add_f32_e32 v27, 1.0, v27
	v_add_f32_e32 v31, 1.0, v31
	v_add_f32_e32 v17, 1.0, v17
	v_add_f32_e32 v21, 1.0, v21
	v_rcp_f32_e32 v19, v19
	v_rcp_f32_e32 v32, v32
	v_rcp_f32_e32 v25, v25
	v_rcp_f32_e32 v29, v29
	v_rcp_f32_e32 v27, v27
	v_rcp_f32_e32 v31, v31
	v_rcp_f32_e32 v17, v17
	v_rcp_f32_e32 v21, v21
	v_add_u32_e32 v22, 0xa0, v144
	v_mad_i64_i32 v[22:23], s[54:55], v22, s53, v[148:149]
	v_lshl_add_u64 v[22:23], v[22:23], 0, v[150:151]
	v_mul_f32_e32 v19, v33, v19
	v_mul_f32_e32 v24, v24, v32
	v_mul_f32_e32 v25, v28, v25
	v_mul_f32_e32 v26, v26, v29
	v_mul_f32_e32 v27, v30, v27
	v_mul_f32_e32 v28, v16, v31
	v_mul_f32_e32 v20, v20, v17
	v_mul_f32_e32 v21, v18, v21
	v_cvt_pk_bf16_f32 v16, v19, v24
	v_cvt_pk_bf16_f32 v17, v25, v26
	v_cvt_pk_bf16_f32 v18, v27, v28
	v_cvt_pk_bf16_f32 v19, v20, v21
	global_store_dwordx4 v[22:23], v[16:19], off
	s_nop 1
	v_pk_mul_f32 v[20:21], v[120:121], v[236:237] op_sel_hi:[1,0]
	v_cvt_f32_i32_e32 v19, v8
	v_cvt_f32_i32_e32 v18, v12
	v_cvt_f32_i32_e32 v8, v13
	v_cvt_f32_i32_e32 v13, v10
	v_cvt_f32_i32_e32 v12, v14
	v_cvt_f32_i32_e32 v10, v15
	v_cvt_f32_i32_e32 v15, v0
	v_cvt_f32_i32_e32 v14, v4
	v_cvt_f32_i32_e32 v0, v5
	v_cvt_f32_i32_e32 v5, v2
	v_cvt_f32_i32_e32 v4, v6
	v_cvt_f32_i32_e32 v2, v7
	v_pk_mul_f32 v[22:23], v[118:119], v[236:237] op_sel_hi:[1,0]
	v_pk_mul_f32 v[24:25], v[122:123], v[236:237] op_sel_hi:[1,0]
	v_pk_mul_f32 v[26:27], v[114:115], v[236:237] op_sel_hi:[1,0]
	v_pk_mul_f32 v[28:29], v[124:125], v[236:237] op_sel_hi:[1,0]
	v_pk_mul_f32 v[30:31], v[116:117], v[236:237] op_sel_hi:[1,0]
	v_pk_mul_f32 v[32:33], v[126:127], v[236:237] op_sel_hi:[1,0]
	v_pk_mul_f32 v[16:17], v[112:113], v[236:237] op_sel_hi:[1,0]
	v_pk_mul_f32 v[18:19], v[20:21], v[18:19]
	v_pk_mul_f32 v[8:9], v[22:23], v[8:9]
	v_pk_mul_f32 v[12:13], v[24:25], v[12:13]
	v_pk_mul_f32 v[10:11], v[26:27], v[10:11]
	v_pk_mul_f32 v[14:15], v[28:29], v[14:15]
	v_pk_mul_f32 v[0:1], v[30:31], v[0:1]
	v_pk_mul_f32 v[4:5], v[32:33], v[4:5]
	v_pk_mul_f32 v[2:3], v[16:17], v[2:3]
	v_mul_f32_e32 v16, 0xbfb8aa3b, v18
	v_mul_f32_e32 v17, v18, v19
	v_mul_f32_e32 v18, 0xbfb8aa3b, v8
	v_mul_f32_e32 v8, v8, v9
	v_mul_f32_e32 v9, 0xbfb8aa3b, v12
	v_mul_f32_e32 v12, v12, v13
	v_mul_f32_e32 v13, 0xbfb8aa3b, v10
	v_mul_f32_e32 v10, v10, v11
	v_mul_f32_e32 v11, 0xbfb8aa3b, v14
	v_mul_f32_e32 v14, v14, v15
	v_mul_f32_e32 v15, 0xbfb8aa3b, v0
	v_mul_f32_e32 v0, v0, v1
	v_mul_f32_e32 v1, 0xbfb8aa3b, v4
	v_mul_f32_e32 v4, v4, v5
	v_mul_f32_e32 v5, 0xbfb8aa3b, v2
	v_mul_f32_e32 v2, v2, v3
	v_exp_f32_e32 v3, v16
	v_exp_f32_e32 v16, v18
	v_exp_f32_e32 v9, v9
	v_exp_f32_e32 v13, v13
	v_exp_f32_e32 v11, v11
	v_exp_f32_e32 v15, v15
	v_exp_f32_e32 v1, v1
	v_exp_f32_e32 v5, v5
	v_add_f32_e32 v3, 1.0, v3
	v_add_f32_e32 v16, 1.0, v16
	v_add_f32_e32 v9, 1.0, v9
	v_add_f32_e32 v13, 1.0, v13
	v_add_f32_e32 v11, 1.0, v11
	v_add_f32_e32 v15, 1.0, v15
	v_add_f32_e32 v1, 1.0, v1
	v_add_f32_e32 v5, 1.0, v5
	v_rcp_f32_e32 v3, v3
	v_rcp_f32_e32 v16, v16
	v_rcp_f32_e32 v9, v9
	v_rcp_f32_e32 v13, v13
	v_rcp_f32_e32 v11, v11
	v_rcp_f32_e32 v15, v15
	v_rcp_f32_e32 v1, v1
	v_rcp_f32_e32 v5, v5
	v_add_u32_e32 v6, 0xb0, v144
	v_mad_i64_i32 v[6:7], s[54:55], v6, s53, v[148:149]
	v_lshl_add_u64 v[6:7], v[6:7], 0, v[150:151]
	v_mul_f32_e32 v3, v17, v3
	v_mul_f32_e32 v8, v8, v16
	v_mul_f32_e32 v9, v12, v9
	v_mul_f32_e32 v10, v10, v13
	v_mul_f32_e32 v11, v14, v11
	v_mul_f32_e32 v12, v0, v15
	v_mul_f32_e32 v4, v4, v1
	v_mul_f32_e32 v5, v2, v5
	v_cvt_pk_bf16_f32 v0, v3, v8
	v_cvt_pk_bf16_f32 v1, v9, v10
	v_cvt_pk_bf16_f32 v2, v11, v12
	v_cvt_pk_bf16_f32 v3, v4, v5
	global_store_dwordx4 v[6:7], v[0:3], off
	s_cbranch_vccnz .LBB0_169
	s_andn2_b64 vcc, exec, s[4:5]
	s_cbranch_vccnz .LBB0_168
	s_barrier
	s_branch .LBB0_168

.LBB0_776:
	v_lshl_or_b32 v170, s47, 7, v154
	v_ashrrev_i32_e32 v171, 31, v170
	v_lshlrev_b64 v[144:145], 2, v[170:171]
	v_lshl_add_u64 v[146:147], s[6:7], 0, v[144:145]
	v_lshl_add_u64 v[144:145], s[10:11], 0, v[144:145]
	global_load_dwordx4 v[148:151], v[146:147], off
	global_load_dwordx4 v[158:161], v[144:145], off
	global_load_dwordx4 v[162:165], v[146:147], off offset:16
	global_load_dwordx4 v[166:169], v[144:145], off offset:16
	v_lshl_add_u32 v144, s28, 8, v152
	v_ashrrev_i32_e32 v145, 31, v144
	v_lshl_add_u64 v[146:147], v[144:145], 2, s[86:87]
	global_load_dword v172, v[146:147], off
	global_load_dword v224, v[146:147], off offset:64
	global_load_dword v226, v[146:147], off offset:128
	global_load_dword v228, v[146:147], off offset:192
	global_load_dword v230, v[146:147], off offset:512
	global_load_dword v232, v[146:147], off offset:576
	global_load_dword v234, v[146:147], off offset:640
	global_load_dword v236, v[146:147], off offset:704
	v_cvt_f32_i32_e32 v175, v120
	v_cvt_f32_i32_e32 v174, v124
	v_cvt_f32_i32_e32 v177, v121
	v_cvt_f32_i32_e32 v176, v125
	v_cvt_f32_i32_e32 v179, v122
	v_cvt_f32_i32_e32 v181, v123
	v_cvt_f32_i32_e32 v186, v118
	v_cvt_f32_i32_e32 v188, v119
	v_cvt_f32_i32_e32 v178, v126
	v_cvt_f32_i32_e32 v180, v127
	v_cvt_f32_i32_e32 v183, v112
	v_cvt_f32_i32_e32 v182, v116
	v_cvt_f32_i32_e32 v185, v113
	v_cvt_f32_i32_e32 v184, v117
	v_cvt_f32_i32_e32 v187, v114
	v_cvt_f32_i32_e32 v189, v115
	v_cvt_f32_i32_e32 v105, v105
	v_cvt_f32_i32_e32 v97, v97
	v_cvt_f32_i32_e32 v107, v107
	v_cvt_f32_i32_e32 v99, v99
	v_cvt_f32_i32_e32 v89, v89
	v_cvt_f32_i32_e32 v91, v91
	v_cvt_f32_i32_e32 v81, v81
	v_cvt_f32_i32_e32 v83, v83
	v_cvt_f32_i32_e32 v73, v73
	v_cvt_f32_i32_e32 v75, v75
	v_cvt_f32_i32_e32 v65, v65
	v_cvt_f32_i32_e32 v67, v67
	v_cvt_f32_i32_e32 v57, v57
	v_cvt_f32_i32_e32 v59, v59
	v_cvt_f32_i32_e32 v49, v49
	v_cvt_f32_i32_e32 v51, v51
	v_cvt_f32_i32_e32 v41, v41
	v_cvt_f32_i32_e32 v43, v43
	v_cvt_f32_i32_e32 v33, v33
	v_cvt_f32_i32_e32 v35, v35
	v_cvt_f32_i32_e32 v25, v25
	v_cvt_f32_i32_e32 v27, v27
	v_cvt_f32_i32_e32 v17, v17
	v_cvt_f32_i32_e32 v19, v19
	v_cvt_f32_i32_e32 v9, v9
	v_cvt_f32_i32_e32 v11, v11
	v_cvt_f32_i32_e32 v1, v1
	v_cvt_f32_i32_e32 v3, v3
	s_andn2_b64 vcc, exec, s[0:1]
	s_mov_b64 s[0:1], -1
	s_mov_b32 s39, s79
	s_waitcnt vmcnt(0)
	v_pk_mul_f32 v[118:119], v[158:159], s[16:17] op_sel_hi:[1,0]
	v_pk_mul_f32 v[122:123], v[148:149], s[16:17] op_sel_hi:[1,0]
	v_mov_b32_e32 v121, v118
	v_mov_b32_e32 v120, v122
	v_pk_mul_f32 v[124:125], v[150:151], s[16:17] op_sel_hi:[1,0]
	v_mov_b32_e32 v118, v123
	v_pk_mul_f32 v[150:151], v[120:121], v[172:173] op_sel_hi:[1,0]
	v_pk_mul_f32 v[114:115], v[160:161], s[16:17] op_sel_hi:[1,0]
	v_pk_mul_f32 v[126:127], v[162:163], s[16:17] op_sel_hi:[1,0]
	v_pk_mul_f32 v[112:113], v[168:169], s[16:17] op_sel_hi:[1,0]
	v_pk_mul_f32 v[116:117], v[166:167], s[16:17] op_sel_hi:[1,0]
	v_pk_mul_f32 v[158:159], v[118:119], v[172:173] op_sel_hi:[1,0]
	v_pk_mul_f32 v[150:151], v[150:151], v[174:175]
	v_pk_mul_f32 v[148:149], v[164:165], s[16:17] op_sel_hi:[1,0]
	v_mov_b32_e32 v122, v124
	v_mov_b32_e32 v123, v114
	v_mov_b32_e32 v114, v125
	v_mov_b32_e32 v125, v116
	v_mov_b32_e32 v116, v127
	v_mov_b32_e32 v127, v112
	v_pk_mul_f32 v[158:159], v[158:159], v[176:177]
	v_mul_f32_e32 v112, 0xbfb8aa3b, v150
	v_mov_b32_e32 v124, v126
	v_mov_b32_e32 v126, v148
	v_pk_mul_f32 v[160:161], v[122:123], v[172:173] op_sel_hi:[1,0]
	v_mul_f32_e32 v148, 0xbfb8aa3b, v158
	v_exp_f32_e32 v112, v112
	v_pk_mul_f32 v[160:161], v[160:161], v[178:179]
	v_exp_f32_e32 v148, v148
	v_mul_f32_e32 v145, v150, v151
	v_mul_f32_e32 v151, 0xbfb8aa3b, v160
	v_exp_f32_e32 v151, v151
	v_add_f32_e32 v112, 1.0, v112
	v_add_f32_e32 v148, 1.0, v148
	v_rcp_f32_e32 v112, v112
	v_pk_mul_f32 v[162:163], v[114:115], v[172:173] op_sel_hi:[1,0]
	v_pk_mul_f32 v[164:165], v[124:125], v[172:173] op_sel_hi:[1,0]
	v_rcp_f32_e32 v148, v148
	v_pk_mul_f32 v[162:163], v[162:163], v[180:181]
	v_pk_mul_f32 v[164:165], v[164:165], v[182:183]
	v_add_f32_e32 v151, 1.0, v151
	v_mul_f32_e32 v150, v158, v159
	v_mul_f32_e32 v158, v160, v161
	v_mul_f32_e32 v159, 0xbfb8aa3b, v162
	v_mul_f32_e32 v161, 0xbfb8aa3b, v164
	v_rcp_f32_e32 v151, v151
	v_exp_f32_e32 v159, v159
	v_exp_f32_e32 v161, v161
	v_mul_f32_e32 v145, v145, v112
	v_mov_b32_e32 v112, v149
	v_pk_mul_f32 v[166:167], v[116:117], v[172:173] op_sel_hi:[1,0]
	v_mul_f32_e32 v150, v150, v148
	v_pk_mul_f32 v[148:149], v[112:113], v[172:173] op_sel_hi:[1,0]
	v_pk_mul_f32 v[168:169], v[126:127], v[172:173] op_sel_hi:[1,0]
	v_pk_mul_f32 v[166:167], v[166:167], v[184:185]
	v_pk_mul_f32 v[148:149], v[148:149], v[188:189]
	v_pk_mul_f32 v[168:169], v[168:169], v[186:187]
	v_mul_f32_e32 v160, v162, v163
	v_mul_f32_e32 v163, 0xbfb8aa3b, v166
	v_mul_f32_e32 v151, v158, v151
	v_mul_f32_e32 v158, 0xbfb8aa3b, v148
	v_mul_f32_e32 v162, v164, v165
	v_mul_f32_e32 v165, 0xbfb8aa3b, v168
	v_exp_f32_e32 v163, v163
	v_add_f32_e32 v159, 1.0, v159
	v_add_f32_e32 v161, 1.0, v161
	v_exp_f32_e32 v158, v158
	v_exp_f32_e32 v165, v165
	v_rcp_f32_e32 v159, v159
	v_rcp_f32_e32 v161, v161
	v_add_f32_e32 v163, 1.0, v163
	v_add_f32_e32 v158, 1.0, v158
	v_rcp_f32_e32 v163, v163
	v_mul_f32_e32 v159, v160, v159
	v_mul_f32_e32 v160, v162, v161
	v_add_f32_e32 v162, 1.0, v165
	v_rcp_f32_e32 v158, v158
	v_rcp_f32_e32 v162, v162
	v_mul_f32_e32 v164, v166, v167
	v_mul_f32_e32 v148, v148, v149
	v_mul_f32_e32 v161, v164, v163
	v_mul_f32_e32 v163, v168, v169
	v_mul_f32_e32 v148, v148, v158
	v_mul_f32_e32 v162, v163, v162
	v_cvt_pk_bf16_f32 v158, v145, v150
	v_cvt_pk_bf16_f32 v159, v151, v159
	v_cvt_pk_bf16_f32 v160, v160, v161
	v_cvt_pk_bf16_f32 v161, v162, v148
	v_mov_b64_e32 v[148:149], s[82:83]
	v_mad_i64_i32 v[162:163], s[30:31], v144, s46, v[148:149]
	v_lshlrev_b64 v[150:151], 1, v[170:171]
	v_lshl_add_u64 v[162:163], v[162:163], 0, v[150:151]
	global_store_dwordx4 v[162:163], v[158:161], off
	v_cvt_f32_i32_e32 v163, v104
	v_cvt_f32_i32_e32 v162, v108
	v_or_b32_e32 v158, 16, v144
	v_ashrrev_i32_e32 v159, 31, v158
	v_lshl_add_u64 v[160:161], v[158:159], 2, s[86:87]
	s_nop 1
	v_cvt_f32_i32_e32 v104, v109
	v_cvt_f32_i32_e32 v109, v106
	v_cvt_f32_i32_e32 v106, v111
	v_cvt_f32_i32_e32 v111, v96
	v_cvt_f32_i32_e32 v96, v101
	v_cvt_f32_i32_e32 v108, v110
	v_cvt_f32_i32_e32 v110, v100
	v_cvt_f32_i32_e32 v101, v98
	v_cvt_f32_i32_e32 v100, v102
	v_cvt_f32_i32_e32 v98, v103
	v_pk_mul_f32 v[102:103], v[120:121], v[224:225] op_sel_hi:[1,0]
	v_pk_mul_f32 v[164:165], v[118:119], v[224:225] op_sel_hi:[1,0]
	v_pk_mul_f32 v[172:173], v[116:117], v[224:225] op_sel_hi:[1,0]
	v_pk_mul_f32 v[102:103], v[102:103], v[162:163]
	v_pk_mul_f32 v[104:105], v[164:165], v[104:105]
	v_pk_mul_f32 v[96:97], v[172:173], v[96:97]
	v_mul_f32_e32 v145, 0xbfb8aa3b, v102
	v_mul_f32_e32 v102, v102, v103
	v_mul_f32_e32 v103, 0xbfb8aa3b, v104
	v_mul_f32_e32 v159, v96, v97
	v_exp_f32_e32 v97, v145
	v_exp_f32_e32 v103, v103
	v_pk_mul_f32 v[166:167], v[122:123], v[224:225] op_sel_hi:[1,0]
	v_pk_mul_f32 v[168:169], v[114:115], v[224:225] op_sel_hi:[1,0]
	v_pk_mul_f32 v[170:171], v[124:125], v[224:225] op_sel_hi:[1,0]
	v_pk_mul_f32 v[174:175], v[126:127], v[224:225] op_sel_hi:[1,0]
	v_pk_mul_f32 v[108:109], v[166:167], v[108:109]
	v_pk_mul_f32 v[106:107], v[168:169], v[106:107]
	v_pk_mul_f32 v[110:111], v[170:171], v[110:111]
	v_pk_mul_f32 v[100:101], v[174:175], v[100:101]
	v_mul_f32_e32 v104, v104, v105
	v_mul_f32_e32 v105, 0xbfb8aa3b, v108
	v_mul_f32_e32 v108, v108, v109
	v_mul_f32_e32 v109, 0xbfb8aa3b, v106
	v_mul_f32_e32 v106, v106, v107
	v_mul_f32_e32 v107, 0xbfb8aa3b, v110
	v_mul_f32_e32 v110, v110, v111
	v_mul_f32_e32 v111, 0xbfb8aa3b, v96
	v_mul_f32_e32 v96, 0xbfb8aa3b, v100
	v_exp_f32_e32 v145, v96
	v_add_f32_e32 v96, 1.0, v97
	v_add_f32_e32 v97, 1.0, v103
	v_rcp_f32_e32 v96, v96
	v_rcp_f32_e32 v97, v97
	v_exp_f32_e32 v105, v105
	v_exp_f32_e32 v109, v109
	v_exp_f32_e32 v107, v107
	v_mul_f32_e32 v102, v102, v96
	v_mul_f32_e32 v104, v104, v97
	v_pk_mul_f32 v[96:97], v[112:113], v[224:225] op_sel_hi:[1,0]
	v_add_f32_e32 v103, 1.0, v105
	v_pk_mul_f32 v[96:97], v[96:97], v[98:99]
	v_add_f32_e32 v105, 1.0, v109
	v_add_f32_e32 v107, 1.0, v107
	v_mul_f32_e32 v98, 0xbfb8aa3b, v96
	v_exp_f32_e32 v111, v111
	v_rcp_f32_e32 v105, v105
	v_rcp_f32_e32 v107, v107
	v_exp_f32_e32 v98, v98
	v_add_f32_e32 v109, 1.0, v111
	v_mul_f32_e32 v105, v106, v105
	v_mul_f32_e32 v106, v110, v107
	v_add_f32_e32 v107, 1.0, v145
	v_add_f32_e32 v98, 1.0, v98
	v_rcp_f32_e32 v109, v109
	v_rcp_f32_e32 v107, v107
	v_rcp_f32_e32 v98, v98
	v_rcp_f32_e32 v103, v103
	v_mul_f32_e32 v100, v100, v101
	v_mul_f32_e32 v96, v96, v97
	v_mul_f32_e32 v99, v159, v109
	v_mul_f32_e32 v100, v100, v107
	v_mul_f32_e32 v101, v96, v98
	v_mul_f32_e32 v103, v108, v103
	v_cvt_pk_bf16_f32 v96, v102, v104
	v_cvt_pk_bf16_f32 v97, v103, v105
	v_cvt_pk_bf16_f32 v98, v106, v99
	v_cvt_pk_bf16_f32 v99, v100, v101
	v_mad_i64_i32 v[100:101], s[30:31], v158, s46, v[148:149]
	v_lshl_add_u64 v[100:101], v[100:101], 0, v[150:151]
	global_store_dwordx4 v[100:101], v[96:99], off
	v_cvt_f32_i32_e32 v101, v88
	v_cvt_f32_i32_e32 v100, v92
	v_or_b32_e32 v96, 32, v144
	v_ashrrev_i32_e32 v97, 31, v96
	v_lshl_add_u64 v[98:99], v[96:97], 2, s[86:87]
	s_nop 1
	v_cvt_f32_i32_e32 v88, v93
	v_cvt_f32_i32_e32 v93, v90
	v_cvt_f32_i32_e32 v92, v94
	v_cvt_f32_i32_e32 v90, v95
	v_cvt_f32_i32_e32 v95, v80
	v_cvt_f32_i32_e32 v94, v84
	v_cvt_f32_i32_e32 v80, v85
	v_cvt_f32_i32_e32 v85, v82
	v_cvt_f32_i32_e32 v84, v86
	v_cvt_f32_i32_e32 v82, v87
	v_pk_mul_f32 v[86:87], v[120:121], v[226:227] op_sel_hi:[1,0]
	v_pk_mul_f32 v[102:103], v[118:119], v[226:227] op_sel_hi:[1,0]
	v_pk_mul_f32 v[104:105], v[122:123], v[226:227] op_sel_hi:[1,0]
	v_pk_mul_f32 v[106:107], v[114:115], v[226:227] op_sel_hi:[1,0]
	v_pk_mul_f32 v[108:109], v[124:125], v[226:227] op_sel_hi:[1,0]
	v_pk_mul_f32 v[86:87], v[86:87], v[100:101]
	v_pk_mul_f32 v[88:89], v[102:103], v[88:89]
	v_pk_mul_f32 v[92:93], v[104:105], v[92:93]
	v_pk_mul_f32 v[90:91], v[106:107], v[90:91]
	v_pk_mul_f32 v[94:95], v[108:109], v[94:95]
	v_mul_f32_e32 v97, 0xbfb8aa3b, v86
	v_mul_f32_e32 v86, v86, v87
	v_mul_f32_e32 v87, 0xbfb8aa3b, v88
	v_mul_f32_e32 v88, v88, v89
	v_mul_f32_e32 v89, 0xbfb8aa3b, v92
	v_mul_f32_e32 v92, v92, v93
	v_mul_f32_e32 v93, 0xbfb8aa3b, v90
	v_mul_f32_e32 v90, v90, v91
	v_mul_f32_e32 v91, 0xbfb8aa3b, v94
	v_pk_mul_f32 v[110:111], v[116:117], v[226:227] op_sel_hi:[1,0]
	v_exp_f32_e32 v87, v87
	v_exp_f32_e32 v89, v89
	v_exp_f32_e32 v93, v93
	v_exp_f32_e32 v91, v91
	v_pk_mul_f32 v[80:81], v[110:111], v[80:81]
	v_mul_f32_e32 v94, v94, v95
	v_mul_f32_e32 v95, 0xbfb8aa3b, v80
	v_exp_f32_e32 v95, v95
	v_add_f32_e32 v87, 1.0, v87
	v_add_f32_e32 v89, 1.0, v89
	v_add_f32_e32 v93, 1.0, v93
	v_add_f32_e32 v91, 1.0, v91
	v_pk_mul_f32 v[158:159], v[126:127], v[226:227] op_sel_hi:[1,0]
	v_rcp_f32_e32 v87, v87
	v_rcp_f32_e32 v89, v89
	v_rcp_f32_e32 v93, v93
	v_rcp_f32_e32 v91, v91
	v_pk_mul_f32 v[98:99], v[112:113], v[226:227] op_sel_hi:[1,0]
	v_pk_mul_f32 v[84:85], v[158:159], v[84:85]
	v_pk_mul_f32 v[82:83], v[98:99], v[82:83]
	v_mul_f32_e32 v80, v80, v81
	v_mul_f32_e32 v81, 0xbfb8aa3b, v84
	v_add_f32_e32 v95, 1.0, v95
	v_mul_f32_e32 v98, 0xbfb8aa3b, v82
	v_exp_f32_e32 v81, v81
	v_rcp_f32_e32 v95, v95
	v_mul_f32_e32 v87, v88, v87
	v_mul_f32_e32 v88, v92, v89
	v_mul_f32_e32 v89, v90, v93
	v_mul_f32_e32 v90, v94, v91
	v_exp_f32_e32 v91, v98
	v_exp_f32_e32 v97, v97
	v_mul_f32_e32 v92, v80, v95
	v_add_f32_e32 v80, 1.0, v81
	v_rcp_f32_e32 v80, v80
	v_add_f32_e32 v81, 1.0, v91
	v_add_f32_e32 v97, 1.0, v97
	v_rcp_f32_e32 v81, v81
	v_rcp_f32_e32 v97, v97
	v_mul_f32_e32 v84, v84, v85
	v_mul_f32_e32 v84, v84, v80
	v_mul_f32_e32 v80, v82, v83
	v_mul_f32_e32 v83, v80, v81
	v_mul_f32_e32 v86, v86, v97
	v_cvt_pk_bf16_f32 v80, v86, v87
	v_cvt_pk_bf16_f32 v81, v88, v89
	v_cvt_pk_bf16_f32 v82, v90, v92
	v_cvt_pk_bf16_f32 v83, v84, v83
	v_mad_i64_i32 v[84:85], s[30:31], v96, s46, v[148:149]
	v_lshl_add_u64 v[84:85], v[84:85], 0, v[150:151]
	global_store_dwordx4 v[84:85], v[80:83], off
	v_cvt_f32_i32_e32 v85, v72
	v_cvt_f32_i32_e32 v84, v76
	v_or_b32_e32 v80, 48, v144
	v_ashrrev_i32_e32 v81, 31, v80
	v_lshl_add_u64 v[82:83], v[80:81], 2, s[86:87]
	s_nop 1
	v_cvt_f32_i32_e32 v72, v77
	v_cvt_f32_i32_e32 v77, v74
	v_cvt_f32_i32_e32 v76, v78
	v_cvt_f32_i32_e32 v74, v79
	v_cvt_f32_i32_e32 v79, v64
	v_cvt_f32_i32_e32 v78, v68
	v_cvt_f32_i32_e32 v64, v69
	v_cvt_f32_i32_e32 v69, v66
	v_cvt_f32_i32_e32 v68, v70
	v_cvt_f32_i32_e32 v66, v71
	v_pk_mul_f32 v[70:71], v[120:121], v[228:229] op_sel_hi:[1,0]
	v_pk_mul_f32 v[86:87], v[118:119], v[228:229] op_sel_hi:[1,0]
	v_pk_mul_f32 v[88:89], v[122:123], v[228:229] op_sel_hi:[1,0]
	v_pk_mul_f32 v[90:91], v[114:115], v[228:229] op_sel_hi:[1,0]
	v_pk_mul_f32 v[92:93], v[124:125], v[228:229] op_sel_hi:[1,0]
	v_pk_mul_f32 v[94:95], v[116:117], v[228:229] op_sel_hi:[1,0]
	v_pk_mul_f32 v[70:71], v[70:71], v[84:85]
	v_pk_mul_f32 v[72:73], v[86:87], v[72:73]
	v_pk_mul_f32 v[76:77], v[88:89], v[76:77]
	v_pk_mul_f32 v[74:75], v[90:91], v[74:75]
	v_pk_mul_f32 v[78:79], v[92:93], v[78:79]
	v_pk_mul_f32 v[64:65], v[94:95], v[64:65]
	v_mul_f32_e32 v81, 0xbfb8aa3b, v70
	v_mul_f32_e32 v70, v70, v71
	v_mul_f32_e32 v71, 0xbfb8aa3b, v72
	v_mul_f32_e32 v72, v72, v73
	v_mul_f32_e32 v73, 0xbfb8aa3b, v76
	v_mul_f32_e32 v76, v76, v77
	v_mul_f32_e32 v77, 0xbfb8aa3b, v74
	v_mul_f32_e32 v74, v74, v75
	v_mul_f32_e32 v75, 0xbfb8aa3b, v78
	v_mul_f32_e32 v78, v78, v79
	v_mul_f32_e32 v79, 0xbfb8aa3b, v64
	v_exp_f32_e32 v71, v71
	v_exp_f32_e32 v73, v73
	v_exp_f32_e32 v77, v77
	v_exp_f32_e32 v75, v75
	v_exp_f32_e32 v79, v79
	v_pk_mul_f32 v[96:97], v[126:127], v[228:229] op_sel_hi:[1,0]
	v_pk_mul_f32 v[82:83], v[112:113], v[228:229] op_sel_hi:[1,0]
	v_pk_mul_f32 v[68:69], v[96:97], v[68:69]
	v_pk_mul_f32 v[66:67], v[82:83], v[66:67]
	v_mul_f32_e32 v64, v64, v65
	v_mul_f32_e32 v65, 0xbfb8aa3b, v68
	v_mul_f32_e32 v82, 0xbfb8aa3b, v66
	v_exp_f32_e32 v65, v65
	v_add_f32_e32 v71, 1.0, v71
	v_add_f32_e32 v73, 1.0, v73
	v_add_f32_e32 v77, 1.0, v77
	v_add_f32_e32 v75, 1.0, v75
	v_add_f32_e32 v79, 1.0, v79
	v_exp_f32_e32 v82, v82
	v_rcp_f32_e32 v71, v71
	v_rcp_f32_e32 v73, v73
	v_rcp_f32_e32 v77, v77
	v_rcp_f32_e32 v75, v75
	v_rcp_f32_e32 v79, v79
	v_exp_f32_e32 v81, v81
	v_add_f32_e32 v65, 1.0, v65
	v_mul_f32_e32 v71, v72, v71
	v_mul_f32_e32 v72, v76, v73
	v_mul_f32_e32 v73, v74, v77
	v_mul_f32_e32 v74, v78, v75
	v_mul_f32_e32 v75, v64, v79
	v_rcp_f32_e32 v64, v65
	v_add_f32_e32 v65, 1.0, v82
	v_add_f32_e32 v81, 1.0, v81
	v_rcp_f32_e32 v65, v65
	v_rcp_f32_e32 v81, v81
	v_mul_f32_e32 v68, v68, v69
	v_mul_f32_e32 v68, v68, v64
	v_mul_f32_e32 v64, v66, v67
	v_mul_f32_e32 v67, v64, v65
	v_mul_f32_e32 v70, v70, v81
	v_cvt_pk_bf16_f32 v64, v70, v71
	v_cvt_pk_bf16_f32 v65, v72, v73
	v_cvt_pk_bf16_f32 v66, v74, v75
	v_cvt_pk_bf16_f32 v67, v68, v67
	v_mad_i64_i32 v[68:69], s[30:31], v80, s46, v[148:149]
	v_lshl_add_u64 v[68:69], v[68:69], 0, v[150:151]
	global_store_dwordx4 v[68:69], v[64:67], off
	s_nop 1
	v_add_u32_e32 v80, 0x80, v144
	v_cvt_f32_i32_e32 v67, v56
	v_cvt_f32_i32_e32 v66, v60
	v_cvt_f32_i32_e32 v56, v61
	v_cvt_f32_i32_e32 v61, v58
	v_cvt_f32_i32_e32 v60, v62
	v_cvt_f32_i32_e32 v58, v63
	v_cvt_f32_i32_e32 v63, v48
	v_cvt_f32_i32_e32 v62, v52
	v_cvt_f32_i32_e32 v48, v53
	v_cvt_f32_i32_e32 v53, v50
	v_cvt_f32_i32_e32 v52, v54
	v_cvt_f32_i32_e32 v50, v55
	v_pk_mul_f32 v[54:55], v[120:121], v[230:231] op_sel_hi:[1,0]
	v_pk_mul_f32 v[68:69], v[118:119], v[230:231] op_sel_hi:[1,0]
	v_pk_mul_f32 v[70:71], v[122:123], v[230:231] op_sel_hi:[1,0]
	v_pk_mul_f32 v[72:73], v[114:115], v[230:231] op_sel_hi:[1,0]
	v_pk_mul_f32 v[74:75], v[124:125], v[230:231] op_sel_hi:[1,0]
	v_pk_mul_f32 v[76:77], v[116:117], v[230:231] op_sel_hi:[1,0]
	v_pk_mul_f32 v[78:79], v[126:127], v[230:231] op_sel_hi:[1,0]
	v_pk_mul_f32 v[64:65], v[112:113], v[230:231] op_sel_hi:[1,0]
	v_pk_mul_f32 v[54:55], v[54:55], v[66:67]
	v_pk_mul_f32 v[56:57], v[68:69], v[56:57]
	v_pk_mul_f32 v[60:61], v[70:71], v[60:61]
	v_pk_mul_f32 v[58:59], v[72:73], v[58:59]
	v_pk_mul_f32 v[62:63], v[74:75], v[62:63]
	v_pk_mul_f32 v[48:49], v[76:77], v[48:49]
	v_pk_mul_f32 v[52:53], v[78:79], v[52:53]
	v_pk_mul_f32 v[50:51], v[64:65], v[50:51]
	v_mul_f32_e32 v64, 0xbfb8aa3b, v54
	v_mul_f32_e32 v54, v54, v55
	v_mul_f32_e32 v55, 0xbfb8aa3b, v56
	v_mul_f32_e32 v56, v56, v57
	v_mul_f32_e32 v57, 0xbfb8aa3b, v60
	v_mul_f32_e32 v60, v60, v61
	v_mul_f32_e32 v61, 0xbfb8aa3b, v58
	v_mul_f32_e32 v58, v58, v59
	v_mul_f32_e32 v59, 0xbfb8aa3b, v62
	v_mul_f32_e32 v62, v62, v63
	v_mul_f32_e32 v63, 0xbfb8aa3b, v48
	v_mul_f32_e32 v48, v48, v49
	v_mul_f32_e32 v49, 0xbfb8aa3b, v52
	v_mul_f32_e32 v52, v52, v53
	v_mul_f32_e32 v53, 0xbfb8aa3b, v50
	v_exp_f32_e32 v55, v55
	v_exp_f32_e32 v57, v57
	v_exp_f32_e32 v61, v61
	v_exp_f32_e32 v59, v59
	v_exp_f32_e32 v63, v63
	v_exp_f32_e32 v49, v49
	v_exp_f32_e32 v53, v53
	v_exp_f32_e32 v64, v64
	v_add_f32_e32 v55, 1.0, v55
	v_add_f32_e32 v57, 1.0, v57
	v_add_f32_e32 v61, 1.0, v61
	v_add_f32_e32 v59, 1.0, v59
	v_add_f32_e32 v63, 1.0, v63
	v_add_f32_e32 v49, 1.0, v49
	v_add_f32_e32 v53, 1.0, v53
	v_rcp_f32_e32 v55, v55
	v_rcp_f32_e32 v57, v57
	v_rcp_f32_e32 v61, v61
	v_rcp_f32_e32 v59, v59
	v_rcp_f32_e32 v63, v63
	v_add_f32_e32 v64, 1.0, v64
	v_rcp_f32_e32 v49, v49
	v_rcp_f32_e32 v53, v53
	v_rcp_f32_e32 v64, v64
	v_mul_f32_e32 v55, v56, v55
	v_mul_f32_e32 v56, v60, v57
	v_mul_f32_e32 v57, v58, v61
	v_mul_f32_e32 v58, v62, v59
	v_mul_f32_e32 v59, v48, v63
	v_mul_f32_e32 v48, v50, v51
	v_mul_f32_e32 v52, v52, v49
	v_mul_f32_e32 v51, v48, v53
	v_mul_f32_e32 v54, v54, v64
	v_cvt_pk_bf16_f32 v48, v54, v55
	v_cvt_pk_bf16_f32 v49, v56, v57
	v_cvt_pk_bf16_f32 v50, v58, v59
	v_cvt_pk_bf16_f32 v51, v52, v51
	v_mad_i64_i32 v[52:53], s[30:31], v80, s46, v[148:149]
	v_lshl_add_u64 v[52:53], v[52:53], 0, v[150:151]
	global_store_dwordx4 v[52:53], v[48:51], off
	s_nop 1
	v_add_u32_e32 v64, 0x90, v144
	v_cvt_f32_i32_e32 v51, v40
	v_cvt_f32_i32_e32 v50, v44
	v_cvt_f32_i32_e32 v40, v45
	v_cvt_f32_i32_e32 v45, v42
	v_cvt_f32_i32_e32 v44, v46
	v_cvt_f32_i32_e32 v42, v47
	v_cvt_f32_i32_e32 v47, v32
	v_cvt_f32_i32_e32 v46, v36
	v_cvt_f32_i32_e32 v32, v37
	v_cvt_f32_i32_e32 v37, v34
	v_cvt_f32_i32_e32 v36, v38
	v_cvt_f32_i32_e32 v34, v39
	v_pk_mul_f32 v[38:39], v[120:121], v[232:233] op_sel_hi:[1,0]
	v_pk_mul_f32 v[52:53], v[118:119], v[232:233] op_sel_hi:[1,0]
	v_pk_mul_f32 v[54:55], v[122:123], v[232:233] op_sel_hi:[1,0]
	v_pk_mul_f32 v[56:57], v[114:115], v[232:233] op_sel_hi:[1,0]
	v_pk_mul_f32 v[58:59], v[124:125], v[232:233] op_sel_hi:[1,0]
	v_pk_mul_f32 v[60:61], v[116:117], v[232:233] op_sel_hi:[1,0]
	v_pk_mul_f32 v[62:63], v[126:127], v[232:233] op_sel_hi:[1,0]
	v_pk_mul_f32 v[48:49], v[112:113], v[232:233] op_sel_hi:[1,0]
	v_pk_mul_f32 v[38:39], v[38:39], v[50:51]
	v_pk_mul_f32 v[40:41], v[52:53], v[40:41]
	v_pk_mul_f32 v[44:45], v[54:55], v[44:45]
	v_pk_mul_f32 v[42:43], v[56:57], v[42:43]
	v_pk_mul_f32 v[46:47], v[58:59], v[46:47]
	v_pk_mul_f32 v[32:33], v[60:61], v[32:33]
	v_pk_mul_f32 v[36:37], v[62:63], v[36:37]
	v_pk_mul_f32 v[34:35], v[48:49], v[34:35]
	v_mul_f32_e32 v48, 0xbfb8aa3b, v38
	v_mul_f32_e32 v38, v38, v39
	v_mul_f32_e32 v39, 0xbfb8aa3b, v40
	v_mul_f32_e32 v40, v40, v41
	v_mul_f32_e32 v41, 0xbfb8aa3b, v44
	v_mul_f32_e32 v44, v44, v45
	v_mul_f32_e32 v45, 0xbfb8aa3b, v42
	v_mul_f32_e32 v42, v42, v43
	v_mul_f32_e32 v43, 0xbfb8aa3b, v46
	v_mul_f32_e32 v46, v46, v47
	v_mul_f32_e32 v47, 0xbfb8aa3b, v32
	v_mul_f32_e32 v32, v32, v33
	v_mul_f32_e32 v33, 0xbfb8aa3b, v36
	v_mul_f32_e32 v36, v36, v37
	v_mul_f32_e32 v37, 0xbfb8aa3b, v34
	v_mul_f32_e32 v34, v34, v35
	v_exp_f32_e32 v35, v48
	v_exp_f32_e32 v33, v33
	v_exp_f32_e32 v37, v37
	v_exp_f32_e32 v39, v39
	v_exp_f32_e32 v41, v41
	v_exp_f32_e32 v45, v45
	v_exp_f32_e32 v43, v43
	v_exp_f32_e32 v47, v47
	v_add_f32_e32 v35, 1.0, v35
	v_add_f32_e32 v33, 1.0, v33
	v_add_f32_e32 v37, 1.0, v37
	v_add_f32_e32 v39, 1.0, v39
	v_add_f32_e32 v41, 1.0, v41
	v_add_f32_e32 v45, 1.0, v45
	v_add_f32_e32 v43, 1.0, v43
	v_add_f32_e32 v47, 1.0, v47
	v_rcp_f32_e32 v35, v35
	v_rcp_f32_e32 v33, v33
	v_rcp_f32_e32 v37, v37
	v_rcp_f32_e32 v39, v39
	v_rcp_f32_e32 v41, v41
	v_rcp_f32_e32 v45, v45
	v_rcp_f32_e32 v43, v43
	v_rcp_f32_e32 v47, v47
	v_mul_f32_e32 v35, v38, v35
	v_mul_f32_e32 v36, v36, v33
	v_mul_f32_e32 v37, v34, v37
	v_mul_f32_e32 v38, v40, v39
	v_mul_f32_e32 v39, v44, v41
	v_mul_f32_e32 v40, v42, v45
	v_mul_f32_e32 v41, v46, v43
	v_mul_f32_e32 v42, v32, v47
	v_cvt_pk_bf16_f32 v32, v35, v38
	v_cvt_pk_bf16_f32 v33, v39, v40
	v_cvt_pk_bf16_f32 v34, v41, v42
	v_cvt_pk_bf16_f32 v35, v36, v37
	v_mad_i64_i32 v[36:37], s[30:31], v64, s46, v[148:149]
	v_lshl_add_u64 v[36:37], v[36:37], 0, v[150:151]
	global_store_dwordx4 v[36:37], v[32:35], off
	s_nop 1
	v_pk_mul_f32 v[36:37], v[120:121], v[234:235] op_sel_hi:[1,0]
	v_cvt_f32_i32_e32 v35, v24
	v_cvt_f32_i32_e32 v34, v28
	v_cvt_f32_i32_e32 v24, v29
	v_cvt_f32_i32_e32 v29, v26
	v_cvt_f32_i32_e32 v28, v30
	v_cvt_f32_i32_e32 v26, v31
	v_cvt_f32_i32_e32 v31, v16
	v_cvt_f32_i32_e32 v30, v20
	v_cvt_f32_i32_e32 v16, v21
	v_cvt_f32_i32_e32 v21, v18
	v_cvt_f32_i32_e32 v20, v22
	v_cvt_f32_i32_e32 v18, v23
	v_pk_mul_f32 v[38:39], v[118:119], v[234:235] op_sel_hi:[1,0]
	v_pk_mul_f32 v[40:41], v[122:123], v[234:235] op_sel_hi:[1,0]
	v_pk_mul_f32 v[42:43], v[114:115], v[234:235] op_sel_hi:[1,0]
	v_pk_mul_f32 v[44:45], v[124:125], v[234:235] op_sel_hi:[1,0]
	v_pk_mul_f32 v[46:47], v[116:117], v[234:235] op_sel_hi:[1,0]
	v_pk_mul_f32 v[48:49], v[126:127], v[234:235] op_sel_hi:[1,0]
	v_pk_mul_f32 v[32:33], v[112:113], v[234:235] op_sel_hi:[1,0]
	v_pk_mul_f32 v[34:35], v[36:37], v[34:35]
	v_pk_mul_f32 v[24:25], v[38:39], v[24:25]
	v_pk_mul_f32 v[28:29], v[40:41], v[28:29]
	v_pk_mul_f32 v[26:27], v[42:43], v[26:27]
	v_pk_mul_f32 v[30:31], v[44:45], v[30:31]
	v_pk_mul_f32 v[16:17], v[46:47], v[16:17]
	v_pk_mul_f32 v[20:21], v[48:49], v[20:21]
	v_pk_mul_f32 v[18:19], v[32:33], v[18:19]
	v_mul_f32_e32 v32, 0xbfb8aa3b, v34
	v_mul_f32_e32 v33, v34, v35
	v_mul_f32_e32 v34, 0xbfb8aa3b, v24
	v_mul_f32_e32 v24, v24, v25
	v_mul_f32_e32 v25, 0xbfb8aa3b, v28
	v_mul_f32_e32 v28, v28, v29
	v_mul_f32_e32 v29, 0xbfb8aa3b, v26
	v_mul_f32_e32 v26, v26, v27
	v_mul_f32_e32 v27, 0xbfb8aa3b, v30
	v_mul_f32_e32 v30, v30, v31
	v_mul_f32_e32 v31, 0xbfb8aa3b, v16
	v_mul_f32_e32 v16, v16, v17
	v_mul_f32_e32 v17, 0xbfb8aa3b, v20
	v_mul_f32_e32 v20, v20, v21
	v_mul_f32_e32 v21, 0xbfb8aa3b, v18
	v_mul_f32_e32 v18, v18, v19
	v_exp_f32_e32 v19, v32
	v_exp_f32_e32 v32, v34
	v_exp_f32_e32 v25, v25
	v_exp_f32_e32 v29, v29
	v_exp_f32_e32 v27, v27
	v_exp_f32_e32 v31, v31
	v_exp_f32_e32 v17, v17
	v_exp_f32_e32 v21, v21
	v_add_f32_e32 v19, 1.0, v19
	v_add_f32_e32 v32, 1.0, v32
	v_add_f32_e32 v25, 1.0, v25
	v_add_f32_e32 v29, 1.0, v29
	v_add_f32_e32 v27, 1.0, v27
	v_add_f32_e32 v31, 1.0, v31
	v_add_f32_e32 v17, 1.0, v17
	v_add_f32_e32 v21, 1.0, v21
	v_rcp_f32_e32 v19, v19
	v_rcp_f32_e32 v32, v32
	v_rcp_f32_e32 v25, v25
	v_rcp_f32_e32 v29, v29
	v_rcp_f32_e32 v27, v27
	v_rcp_f32_e32 v31, v31
	v_rcp_f32_e32 v17, v17
	v_rcp_f32_e32 v21, v21
	v_add_u32_e32 v22, 0xa0, v144
	v_mad_i64_i32 v[22:23], s[30:31], v22, s46, v[148:149]
	v_lshl_add_u64 v[22:23], v[22:23], 0, v[150:151]
	v_mul_f32_e32 v19, v33, v19
	v_mul_f32_e32 v24, v24, v32
	v_mul_f32_e32 v25, v28, v25
	v_mul_f32_e32 v26, v26, v29
	v_mul_f32_e32 v27, v30, v27
	v_mul_f32_e32 v28, v16, v31
	v_mul_f32_e32 v20, v20, v17
	v_mul_f32_e32 v21, v18, v21
	v_cvt_pk_bf16_f32 v16, v19, v24
	v_cvt_pk_bf16_f32 v17, v25, v26
	v_cvt_pk_bf16_f32 v18, v27, v28
	v_cvt_pk_bf16_f32 v19, v20, v21
	global_store_dwordx4 v[22:23], v[16:19], off
	s_nop 1
	v_pk_mul_f32 v[20:21], v[120:121], v[236:237] op_sel_hi:[1,0]
	v_cvt_f32_i32_e32 v19, v8
	v_cvt_f32_i32_e32 v18, v12
	v_cvt_f32_i32_e32 v8, v13
	v_cvt_f32_i32_e32 v13, v10
	v_cvt_f32_i32_e32 v12, v14
	v_cvt_f32_i32_e32 v10, v15
	v_cvt_f32_i32_e32 v15, v0
	v_cvt_f32_i32_e32 v14, v4
	v_cvt_f32_i32_e32 v0, v5
	v_cvt_f32_i32_e32 v5, v2
	v_cvt_f32_i32_e32 v4, v6
	v_cvt_f32_i32_e32 v2, v7
	v_pk_mul_f32 v[22:23], v[118:119], v[236:237] op_sel_hi:[1,0]
	v_pk_mul_f32 v[24:25], v[122:123], v[236:237] op_sel_hi:[1,0]
	v_pk_mul_f32 v[26:27], v[114:115], v[236:237] op_sel_hi:[1,0]
	v_pk_mul_f32 v[28:29], v[124:125], v[236:237] op_sel_hi:[1,0]
	v_pk_mul_f32 v[30:31], v[116:117], v[236:237] op_sel_hi:[1,0]
	v_pk_mul_f32 v[32:33], v[126:127], v[236:237] op_sel_hi:[1,0]
	v_pk_mul_f32 v[16:17], v[112:113], v[236:237] op_sel_hi:[1,0]
	v_pk_mul_f32 v[18:19], v[20:21], v[18:19]
	v_pk_mul_f32 v[8:9], v[22:23], v[8:9]
	v_pk_mul_f32 v[12:13], v[24:25], v[12:13]
	v_pk_mul_f32 v[10:11], v[26:27], v[10:11]
	v_pk_mul_f32 v[14:15], v[28:29], v[14:15]
	v_pk_mul_f32 v[0:1], v[30:31], v[0:1]
	v_pk_mul_f32 v[4:5], v[32:33], v[4:5]
	v_pk_mul_f32 v[2:3], v[16:17], v[2:3]
	v_mul_f32_e32 v16, 0xbfb8aa3b, v18
	v_mul_f32_e32 v17, v18, v19
	v_mul_f32_e32 v18, 0xbfb8aa3b, v8
	v_mul_f32_e32 v8, v8, v9
	v_mul_f32_e32 v9, 0xbfb8aa3b, v12
	v_mul_f32_e32 v12, v12, v13
	v_mul_f32_e32 v13, 0xbfb8aa3b, v10
	v_mul_f32_e32 v10, v10, v11
	v_mul_f32_e32 v11, 0xbfb8aa3b, v14
	v_mul_f32_e32 v14, v14, v15
	v_mul_f32_e32 v15, 0xbfb8aa3b, v0
	v_mul_f32_e32 v0, v0, v1
	v_mul_f32_e32 v1, 0xbfb8aa3b, v4
	v_mul_f32_e32 v4, v4, v5
	v_mul_f32_e32 v5, 0xbfb8aa3b, v2
	v_mul_f32_e32 v2, v2, v3
	v_exp_f32_e32 v3, v16
	v_exp_f32_e32 v16, v18
	v_exp_f32_e32 v9, v9
	v_exp_f32_e32 v13, v13
	v_exp_f32_e32 v11, v11
	v_exp_f32_e32 v15, v15
	v_exp_f32_e32 v1, v1
	v_exp_f32_e32 v5, v5
	v_add_f32_e32 v3, 1.0, v3
	v_add_f32_e32 v16, 1.0, v16
	v_add_f32_e32 v9, 1.0, v9
	v_add_f32_e32 v13, 1.0, v13
	v_add_f32_e32 v11, 1.0, v11
	v_add_f32_e32 v15, 1.0, v15
	v_add_f32_e32 v1, 1.0, v1
	v_add_f32_e32 v5, 1.0, v5
	v_rcp_f32_e32 v3, v3
	v_rcp_f32_e32 v16, v16
	v_rcp_f32_e32 v9, v9
	v_rcp_f32_e32 v13, v13
	v_rcp_f32_e32 v11, v11
	v_rcp_f32_e32 v15, v15
	v_rcp_f32_e32 v1, v1
	v_rcp_f32_e32 v5, v5
	v_add_u32_e32 v6, 0xb0, v144
	v_mad_i64_i32 v[6:7], s[30:31], v6, s46, v[148:149]
	v_lshl_add_u64 v[6:7], v[6:7], 0, v[150:151]
	v_mul_f32_e32 v3, v17, v3
	v_mul_f32_e32 v8, v8, v16
	v_mul_f32_e32 v9, v12, v9
	v_mul_f32_e32 v10, v10, v13
	v_mul_f32_e32 v11, v14, v11
	v_mul_f32_e32 v12, v0, v15
	v_mul_f32_e32 v4, v4, v1
	v_mul_f32_e32 v5, v2, v5
	v_cvt_pk_bf16_f32 v0, v3, v8
	v_cvt_pk_bf16_f32 v1, v9, v10
	v_cvt_pk_bf16_f32 v2, v11, v12
	v_cvt_pk_bf16_f32 v3, v4, v5
	global_store_dwordx4 v[6:7], v[0:3], off
	s_cbranch_vccnz .LBB0_769
	s_andn2_b64 vcc, exec, s[4:5]
	s_cbranch_vccnz .LBB0_768
	s_barrier
	s_branch .LBB0_768
